# GEMM epilogue (Y,G) stores write-through sc1 so grid barriers find a clean L2; plus 160-row balanced P3/P7/P10 and relocated helper conversions
# speedup vs baseline: 1.0228x; 1.0193x over previous
.LBB0_173:
	v_mul_f32_e32 v149, 0xbfb8aa3b, v126
	v_exp_f32_e32 v150, v149
	v_mul_f32_e32 v149, 0xbfb8aa3b, v127
	v_pk_mul_f32 v[122:123], v[126:127], v[122:123]
	v_mul_f32_e32 v126, 0xbfb8aa3b, v128
	v_mul_f32_e32 v127, 0xbfb8aa3b, v129
	v_exp_f32_e32 v126, v126
	v_exp_f32_e32 v127, v127
	v_pk_mul_f32 v[124:125], v[128:129], v[124:125]
	v_mul_f32_e32 v129, 0xbfb8aa3b, v119
	v_add_f32_e32 v126, 1.0, v126
	v_add_f32_e32 v127, 1.0, v127
	v_rcp_f32_e32 v126, v126
	v_rcp_f32_e32 v127, v127
	v_pk_mul_f32 v[114:115], v[118:119], v[114:115]
	v_pk_mul_f32 v[106:107], v[110:111], v[106:107]
	v_pk_mul_f32 v[108:109], v[112:113], v[108:109]
	v_pk_mul_f32 v[124:125], v[126:127], v[124:125]
	v_pk_mul_f32 v[100:101], v[104:105], v[100:101]
	v_cvt_pk_bf16_f32 v119, v124, v125
	v_mul_f32_e32 v124, 0xbfb8aa3b, v110
	v_mul_f32_e32 v125, 0xbfb8aa3b, v111
	v_mul_f32_e32 v110, 0xbfb8aa3b, v112
	v_mul_f32_e32 v111, 0xbfb8aa3b, v113
	v_exp_f32_e32 v110, v110
	v_exp_f32_e32 v111, v111
	v_mul_f32_e32 v112, 0xbfb8aa3b, v102
	v_mul_f32_e32 v113, 0xbfb8aa3b, v103
	v_add_f32_e32 v110, 1.0, v110
	v_add_f32_e32 v111, 1.0, v111
	v_rcp_f32_e32 v110, v110
	v_rcp_f32_e32 v111, v111
	v_exp_f32_e32 v112, v112
	v_exp_f32_e32 v113, v113
	v_pk_mul_f32 v[90:91], v[94:95], v[90:91]
	v_pk_mul_f32 v[108:109], v[110:111], v[108:109]
	v_add_f32_e32 v110, 1.0, v112
	v_add_f32_e32 v111, 1.0, v113
	v_mul_f32_e32 v112, 0xbfb8aa3b, v104
	v_mul_f32_e32 v113, 0xbfb8aa3b, v105
	v_exp_f32_e32 v112, v112
	v_exp_f32_e32 v113, v113
	v_mul_f32_e32 v128, 0xbfb8aa3b, v118
	v_pk_mul_f32 v[92:93], v[96:97], v[92:93]
	v_add_f32_e32 v112, 1.0, v112
	v_add_f32_e32 v113, 1.0, v113
	v_rcp_f32_e32 v112, v112
	v_rcp_f32_e32 v113, v113
	v_exp_f32_e32 v128, v128
	v_exp_f32_e32 v129, v129
	v_exp_f32_e32 v151, v149
	v_pk_mul_f32 v[104:105], v[112:113], v[100:101]
	v_add_f32_e32 v126, 1.0, v128
	v_cvt_pk_bf16_f32 v101, v104, v105
	v_mul_f32_e32 v104, 0xbfb8aa3b, v94
	v_mul_f32_e32 v105, 0xbfb8aa3b, v95
	v_mul_f32_e32 v94, 0xbfb8aa3b, v96
	v_mul_f32_e32 v95, 0xbfb8aa3b, v97
	v_exp_f32_e32 v94, v94
	v_exp_f32_e32 v95, v95
	v_mul_f32_e32 v96, 0xbfb8aa3b, v86
	v_mul_f32_e32 v97, 0xbfb8aa3b, v87
	v_add_f32_e32 v94, 1.0, v94
	v_add_f32_e32 v95, 1.0, v95
	v_rcp_f32_e32 v94, v94
	v_rcp_f32_e32 v95, v95
	v_exp_f32_e32 v96, v96
	v_exp_f32_e32 v97, v97
	v_add_f32_e32 v127, 1.0, v129
	v_mul_f32_e32 v128, 0xbfb8aa3b, v120
	v_mul_f32_e32 v129, 0xbfb8aa3b, v121
	v_pk_mul_f32 v[92:93], v[94:95], v[92:93]
	v_add_f32_e32 v94, 1.0, v96
	v_add_f32_e32 v95, 1.0, v97
	v_mul_f32_e32 v96, 0xbfb8aa3b, v88
	v_mul_f32_e32 v97, 0xbfb8aa3b, v89
	v_exp_f32_e32 v128, v128
	v_exp_f32_e32 v129, v129
	v_exp_f32_e32 v96, v96
	v_exp_f32_e32 v97, v97
	v_add_f32_e32 v150, 1.0, v150
	v_add_f32_e32 v151, 1.0, v151
	v_rcp_f32_e32 v126, v126
	v_rcp_f32_e32 v127, v127
	v_add_f32_e32 v128, 1.0, v128
	v_add_f32_e32 v129, 1.0, v129
	v_add_f32_e32 v96, 1.0, v96
	v_add_f32_e32 v97, 1.0, v97
	v_rcp_f32_e32 v150, v150
	v_rcp_f32_e32 v151, v151
	v_rcp_f32_e32 v128, v128
	v_rcp_f32_e32 v129, v129
	v_rcp_f32_e32 v96, v96
	v_rcp_f32_e32 v97, v97
	v_lshl_or_b32 v148, s77, 7, v143
	v_pk_mul_f32 v[116:117], v[120:121], v[116:117]
	v_pk_mul_f32 v[114:115], v[126:127], v[114:115]
	v_exp_f32_e32 v124, v124
	v_exp_f32_e32 v125, v125
	v_pk_mul_f32 v[84:85], v[88:89], v[84:85]
	v_lshl_add_u32 v147, s62, 8, v1
	v_ashrrev_i32_e32 v149, 31, v148
	v_pk_mul_f32 v[122:123], v[150:151], v[122:123]
	v_pk_mul_f32 v[116:117], v[128:129], v[116:117]
	v_cvt_pk_bf16_f32 v120, v114, v115
	v_mov_b64_e32 v[114:115], s[40:41]
	v_pk_mul_f32 v[88:89], v[96:97], v[84:85]
	v_cvt_pk_bf16_f32 v118, v122, v123
	v_cvt_pk_bf16_f32 v121, v116, v117
	v_mad_i64_i32 v[122:123], s[64:65], v147, s76, v[114:115]
	v_lshlrev_b64 v[116:117], 1, v[148:149]
	v_cvt_pk_bf16_f32 v85, v88, v89
	v_mul_f32_e32 v88, 0xbfb8aa3b, v78
	v_mul_f32_e32 v89, 0xbfb8aa3b, v79
	v_pk_mul_f32 v[74:75], v[78:79], v[74:75]
	v_mul_f32_e32 v78, 0xbfb8aa3b, v80
	v_mul_f32_e32 v79, 0xbfb8aa3b, v81
	v_lshl_add_u64 v[122:123], v[122:123], 0, v[116:117]
	v_rcp_f32_e32 v110, v110
	v_rcp_f32_e32 v111, v111
	v_exp_f32_e32 v78, v78
	v_exp_f32_e32 v79, v79
	global_store_dwordx4 v[122:123], v[118:121], off sc1
	v_pk_mul_f32 v[98:99], v[102:103], v[98:99]
	v_exp_f32_e32 v104, v104
	v_add_f32_e32 v118, 1.0, v124
	v_add_f32_e32 v119, 1.0, v125
	v_rcp_f32_e32 v118, v118
	v_rcp_f32_e32 v119, v119
	v_pk_mul_f32 v[102:103], v[110:111], v[98:99]
	v_exp_f32_e32 v105, v105
	v_pk_mul_f32 v[76:77], v[80:81], v[76:77]
	v_add_f32_e32 v78, 1.0, v78
	v_add_f32_e32 v79, 1.0, v79
	v_mul_f32_e32 v80, 0xbfb8aa3b, v70
	v_mul_f32_e32 v81, 0xbfb8aa3b, v71
	v_cvt_pk_bf16_f32 v100, v102, v103
	v_or_b32_e32 v102, 16, v147
	v_rcp_f32_e32 v78, v78
	v_rcp_f32_e32 v79, v79
	v_exp_f32_e32 v80, v80
	v_exp_f32_e32 v81, v81
	v_pk_mul_f32 v[106:107], v[118:119], v[106:107]
	v_mad_i64_i32 v[102:103], s[64:65], v102, s76, v[114:115]
	v_cvt_pk_bf16_f32 v98, v106, v107
	v_cvt_pk_bf16_f32 v99, v108, v109
	v_lshl_add_u64 v[102:103], v[102:103], 0, v[116:117]
	v_rcp_f32_e32 v94, v94
	v_rcp_f32_e32 v95, v95
	global_store_dwordx4 v[102:103], v[98:101], off sc1
	v_pk_mul_f32 v[76:77], v[78:79], v[76:77]
	v_add_f32_e32 v78, 1.0, v80
	v_add_f32_e32 v98, 1.0, v104
	v_add_f32_e32 v99, 1.0, v105
	v_rcp_f32_e32 v98, v98
	v_rcp_f32_e32 v99, v99
	v_add_f32_e32 v79, 1.0, v81
	v_mul_f32_e32 v80, 0xbfb8aa3b, v72
	v_mul_f32_e32 v81, 0xbfb8aa3b, v73
	v_pk_mul_f32 v[82:83], v[86:87], v[82:83]
	v_exp_f32_e32 v80, v80
	v_exp_f32_e32 v81, v81
	v_pk_mul_f32 v[86:87], v[94:95], v[82:83]
	v_exp_f32_e32 v88, v88
	v_exp_f32_e32 v89, v89
	v_cvt_pk_bf16_f32 v84, v86, v87
	v_or_b32_e32 v86, 32, v147
	v_pk_mul_f32 v[90:91], v[98:99], v[90:91]
	v_mad_i64_i32 v[86:87], s[64:65], v86, s76, v[114:115]
	v_cvt_pk_bf16_f32 v82, v90, v91
	v_cvt_pk_bf16_f32 v83, v92, v93
	v_lshl_add_u64 v[86:87], v[86:87], 0, v[116:117]
	v_rcp_f32_e32 v78, v78
	v_rcp_f32_e32 v79, v79
	v_add_f32_e32 v80, 1.0, v80
	v_add_f32_e32 v81, 1.0, v81
	global_store_dwordx4 v[86:87], v[82:85], off sc1
	v_rcp_f32_e32 v80, v80
	v_rcp_f32_e32 v81, v81
	v_add_f32_e32 v82, 1.0, v88
	v_add_f32_e32 v83, 1.0, v89
	v_rcp_f32_e32 v82, v82
	v_rcp_f32_e32 v83, v83
	v_pk_mul_f32 v[66:67], v[70:71], v[66:67]
	v_pk_mul_f32 v[68:69], v[72:73], v[68:69]
	v_pk_mul_f32 v[70:71], v[78:79], v[66:67]
	v_pk_mul_f32 v[72:73], v[80:81], v[68:69]
	v_cvt_pk_bf16_f32 v68, v70, v71
	v_or_b32_e32 v70, 48, v147
	v_pk_mul_f32 v[74:75], v[82:83], v[74:75]
	v_mad_i64_i32 v[70:71], s[64:65], v70, s76, v[114:115]
	v_cvt_pk_bf16_f32 v66, v74, v75
	v_cvt_pk_bf16_f32 v67, v76, v77
	v_cvt_pk_bf16_f32 v69, v72, v73
	v_lshl_add_u64 v[70:71], v[70:71], 0, v[116:117]
	global_store_dwordx4 v[70:71], v[66:69], off sc1
	v_pk_mul_f32 v[58:59], v[62:63], v[58:59]
	v_pk_mul_f32 v[60:61], v[64:65], v[60:61]
	v_mul_f32_e32 v66, 0xbfb8aa3b, v62
	v_mul_f32_e32 v67, 0xbfb8aa3b, v63
	v_mul_f32_e32 v62, 0xbfb8aa3b, v64
	v_mul_f32_e32 v63, 0xbfb8aa3b, v65
	v_exp_f32_e32 v62, v62
	v_exp_f32_e32 v63, v63
	v_mul_f32_e32 v64, 0xbfb8aa3b, v54
	v_mul_f32_e32 v65, 0xbfb8aa3b, v55
	v_add_f32_e32 v62, 1.0, v62
	v_add_f32_e32 v63, 1.0, v63
	v_rcp_f32_e32 v62, v62
	v_rcp_f32_e32 v63, v63
	v_exp_f32_e32 v64, v64
	v_exp_f32_e32 v65, v65
	v_pk_mul_f32 v[52:53], v[56:57], v[52:53]
	v_pk_mul_f32 v[60:61], v[62:63], v[60:61]
	v_add_f32_e32 v62, 1.0, v64
	v_add_f32_e32 v63, 1.0, v65
	v_mul_f32_e32 v64, 0xbfb8aa3b, v56
	v_mul_f32_e32 v65, 0xbfb8aa3b, v57
	v_exp_f32_e32 v64, v64
	v_exp_f32_e32 v65, v65
	v_pk_mul_f32 v[42:43], v[46:47], v[42:43]
	v_pk_mul_f32 v[44:45], v[48:49], v[44:45]
	v_add_f32_e32 v64, 1.0, v64
	v_add_f32_e32 v65, 1.0, v65
	v_rcp_f32_e32 v64, v64
	v_rcp_f32_e32 v65, v65
	v_pk_mul_f32 v[36:37], v[40:41], v[36:37]
	v_pk_mul_f32 v[26:27], v[30:31], v[26:27]
	v_pk_mul_f32 v[28:29], v[32:33], v[28:29]
	v_pk_mul_f32 v[56:57], v[64:65], v[52:53]
	v_exp_f32_e32 v66, v66
	v_cvt_pk_bf16_f32 v53, v56, v57
	v_mul_f32_e32 v56, 0xbfb8aa3b, v46
	v_mul_f32_e32 v57, 0xbfb8aa3b, v47
	v_mul_f32_e32 v46, 0xbfb8aa3b, v48
	v_mul_f32_e32 v47, 0xbfb8aa3b, v49
	v_exp_f32_e32 v46, v46
	v_exp_f32_e32 v47, v47
	v_mul_f32_e32 v48, 0xbfb8aa3b, v38
	v_mul_f32_e32 v49, 0xbfb8aa3b, v39
	v_add_f32_e32 v46, 1.0, v46
	v_add_f32_e32 v47, 1.0, v47
	v_rcp_f32_e32 v46, v46
	v_rcp_f32_e32 v47, v47
	v_exp_f32_e32 v48, v48
	v_exp_f32_e32 v49, v49
	v_exp_f32_e32 v67, v67
	v_pk_mul_f32 v[44:45], v[46:47], v[44:45]
	v_add_f32_e32 v46, 1.0, v48
	v_add_f32_e32 v47, 1.0, v49
	v_mul_f32_e32 v48, 0xbfb8aa3b, v40
	v_mul_f32_e32 v49, 0xbfb8aa3b, v41
	v_exp_f32_e32 v48, v48
	v_exp_f32_e32 v49, v49
	v_add_f32_e32 v66, 1.0, v66
	v_add_f32_e32 v67, 1.0, v67
	v_add_f32_e32 v48, 1.0, v48
	v_add_f32_e32 v49, 1.0, v49
	v_rcp_f32_e32 v48, v48
	v_rcp_f32_e32 v49, v49
	v_rcp_f32_e32 v62, v62
	v_rcp_f32_e32 v63, v63
	v_rcp_f32_e32 v66, v66
	v_pk_mul_f32 v[40:41], v[48:49], v[36:37]
	v_rcp_f32_e32 v67, v67
	v_cvt_pk_bf16_f32 v37, v40, v41
	v_mul_f32_e32 v40, 0xbfb8aa3b, v30
	v_mul_f32_e32 v41, 0xbfb8aa3b, v31
	v_mul_f32_e32 v30, 0xbfb8aa3b, v32
	v_mul_f32_e32 v31, 0xbfb8aa3b, v33
	v_exp_f32_e32 v30, v30
	v_exp_f32_e32 v31, v31
	v_mul_f32_e32 v32, 0xbfb8aa3b, v22
	v_mul_f32_e32 v33, 0xbfb8aa3b, v23
	v_add_f32_e32 v30, 1.0, v30
	v_add_f32_e32 v31, 1.0, v31
	v_rcp_f32_e32 v30, v30
	v_rcp_f32_e32 v31, v31
	v_exp_f32_e32 v32, v32
	v_exp_f32_e32 v33, v33
	v_pk_mul_f32 v[50:51], v[54:55], v[50:51]
	v_pk_mul_f32 v[28:29], v[30:31], v[28:29]
	v_add_f32_e32 v30, 1.0, v32
	v_add_f32_e32 v31, 1.0, v33
	v_mul_f32_e32 v32, 0xbfb8aa3b, v24
	v_mul_f32_e32 v33, 0xbfb8aa3b, v25
	v_exp_f32_e32 v32, v32
	v_exp_f32_e32 v33, v33
	v_exp_f32_e32 v56, v56
	v_exp_f32_e32 v57, v57
	v_add_f32_e32 v32, 1.0, v32
	v_add_f32_e32 v33, 1.0, v33
	v_rcp_f32_e32 v32, v32
	v_rcp_f32_e32 v33, v33
	v_pk_mul_f32 v[20:21], v[24:25], v[20:21]
	v_add_u32_e32 v68, 0x80, v147
	v_pk_mul_f32 v[54:55], v[62:63], v[50:51]
	v_pk_mul_f32 v[24:25], v[32:33], v[20:21]
	v_pk_mul_f32 v[58:59], v[66:67], v[58:59]
	v_cvt_pk_bf16_f32 v52, v54, v55
	v_mad_i64_i32 v[54:55], s[64:65], v68, s76, v[114:115]
	v_cvt_pk_bf16_f32 v21, v24, v25
	v_mul_f32_e32 v24, 0xbfb8aa3b, v14
	v_mul_f32_e32 v25, 0xbfb8aa3b, v15
	v_pk_mul_f32 v[10:11], v[14:15], v[10:11]
	v_mul_f32_e32 v14, 0xbfb8aa3b, v16
	v_mul_f32_e32 v15, 0xbfb8aa3b, v17
	v_cvt_pk_bf16_f32 v50, v58, v59
	v_cvt_pk_bf16_f32 v51, v60, v61
	v_lshl_add_u64 v[54:55], v[54:55], 0, v[116:117]
	v_rcp_f32_e32 v46, v46
	v_rcp_f32_e32 v47, v47
	v_exp_f32_e32 v14, v14
	v_exp_f32_e32 v15, v15
	global_store_dwordx4 v[54:55], v[50:53], off sc1
	v_pk_mul_f32 v[34:35], v[38:39], v[34:35]
	v_exp_f32_e32 v40, v40
	v_add_f32_e32 v50, 1.0, v56
	v_add_f32_e32 v51, 1.0, v57
	v_rcp_f32_e32 v50, v50
	v_rcp_f32_e32 v51, v51
	v_pk_mul_f32 v[38:39], v[46:47], v[34:35]
	v_exp_f32_e32 v41, v41
	v_pk_mul_f32 v[12:13], v[16:17], v[12:13]
	v_add_f32_e32 v14, 1.0, v14
	v_add_f32_e32 v15, 1.0, v15
	v_mul_f32_e32 v16, 0xbfb8aa3b, v6
	v_mul_f32_e32 v17, 0xbfb8aa3b, v7
	v_cvt_pk_bf16_f32 v36, v38, v39
	v_add_u32_e32 v38, 0x90, v147
	v_rcp_f32_e32 v14, v14
	v_rcp_f32_e32 v15, v15
	v_exp_f32_e32 v16, v16
	v_exp_f32_e32 v17, v17
	v_pk_mul_f32 v[42:43], v[50:51], v[42:43]
	v_mad_i64_i32 v[38:39], s[64:65], v38, s76, v[114:115]
	v_cvt_pk_bf16_f32 v34, v42, v43
	v_cvt_pk_bf16_f32 v35, v44, v45
	v_lshl_add_u64 v[38:39], v[38:39], 0, v[116:117]
	v_rcp_f32_e32 v30, v30
	v_rcp_f32_e32 v31, v31
	global_store_dwordx4 v[38:39], v[34:37], off sc1
	v_pk_mul_f32 v[12:13], v[14:15], v[12:13]
	v_add_f32_e32 v14, 1.0, v16
	v_add_f32_e32 v34, 1.0, v40
	v_add_f32_e32 v35, 1.0, v41
	v_rcp_f32_e32 v34, v34
	v_rcp_f32_e32 v35, v35
	v_add_f32_e32 v15, 1.0, v17
	v_mul_f32_e32 v16, 0xbfb8aa3b, v8
	v_mul_f32_e32 v17, 0xbfb8aa3b, v9
	v_pk_mul_f32 v[18:19], v[22:23], v[18:19]
	v_exp_f32_e32 v16, v16
	v_exp_f32_e32 v17, v17
	v_pk_mul_f32 v[22:23], v[30:31], v[18:19]
	v_exp_f32_e32 v24, v24
	v_exp_f32_e32 v25, v25
	v_cvt_pk_bf16_f32 v20, v22, v23
	v_add_u32_e32 v22, 0xa0, v147
	v_pk_mul_f32 v[26:27], v[34:35], v[26:27]
	v_mad_i64_i32 v[22:23], s[64:65], v22, s76, v[114:115]
	v_cvt_pk_bf16_f32 v18, v26, v27
	v_cvt_pk_bf16_f32 v19, v28, v29
	v_lshl_add_u64 v[22:23], v[22:23], 0, v[116:117]
	v_rcp_f32_e32 v14, v14
	v_rcp_f32_e32 v15, v15
	v_add_f32_e32 v16, 1.0, v16
	v_add_f32_e32 v17, 1.0, v17
	global_store_dwordx4 v[22:23], v[18:21], off sc1
	v_rcp_f32_e32 v16, v16
	v_rcp_f32_e32 v17, v17
	v_add_f32_e32 v18, 1.0, v24
	v_add_f32_e32 v19, 1.0, v25
	v_rcp_f32_e32 v18, v18
	v_rcp_f32_e32 v19, v19
	v_pk_mul_f32 v[2:3], v[6:7], v[2:3]
	v_pk_mul_f32 v[4:5], v[8:9], v[4:5]
	v_pk_mul_f32 v[6:7], v[14:15], v[2:3]
	v_pk_mul_f32 v[8:9], v[16:17], v[4:5]
	v_cvt_pk_bf16_f32 v4, v6, v7
	v_add_u32_e32 v6, 0xb0, v147
	v_pk_mul_f32 v[10:11], v[18:19], v[10:11]
	v_mad_i64_i32 v[6:7], s[64:65], v6, s76, v[114:115]
	v_cvt_pk_bf16_f32 v2, v10, v11
	v_cvt_pk_bf16_f32 v3, v12, v13
	v_cvt_pk_bf16_f32 v5, v8, v9
	v_lshl_add_u64 v[6:7], v[6:7], 0, v[116:117]
	s_andn2_b64 vcc, exec, s[0:1]
	s_mov_b64 s[0:1], -1
	global_store_dwordx4 v[6:7], v[2:5], off sc1
	s_cbranch_vccnz .LBB0_166
	s_andn2_b64 vcc, exec, s[6:7]
	s_cbranch_vccnz .LBB0_165
	s_barrier
	s_branch .LBB0_165

.LBB0_260:
	s_mul_i32 s98, s81, 0xa0
	v_lshl_or_b32 v216, s82, 8, v143
	v_add_u32_e32 v214, s98, v1
	v_ashrrev_i32_e32 v217, 31, v216
	v_ashrrev_i32_e32 v215, 31, v214
	v_lshlrev_b64 v[216:217], 1, v[216:217]
	v_lshlrev_b64 v[218:219], 11, v[214:215]
	v_lshl_add_u64 v[218:219], s[42:43], 0, v[218:219]
	v_lshl_add_u64 v[218:219], v[218:219], 0, v[216:217]
	v_cvt_pk_bf16_f32 v166, v126, v127
	v_cvt_pk_bf16_f32 v167, v128, v129
	v_cvt_pk_bf16_f32 v168, v122, v123
	v_cvt_pk_bf16_f32 v169, v124, v125
	global_store_dwordx4 v[218:219], v[166:169], off sc1
	v_cvt_pk_bf16_f32 v170, v110, v111
	v_cvt_pk_bf16_f32 v171, v112, v113
	v_cvt_pk_bf16_f32 v172, v106, v107
	v_cvt_pk_bf16_f32 v173, v108, v109
	global_store_dwordx4 v[218:219], v[170:173], off offset:256 sc1
	v_mov_b32_e32 v148, 0x8000
	v_mov_b32_e32 v149, 0
	v_lshl_add_u64 v[148:149], v[218:219], 0, v[148:149]
	v_cvt_pk_bf16_f32 v174, v118, v119
	v_cvt_pk_bf16_f32 v175, v120, v121
	v_cvt_pk_bf16_f32 v176, v114, v115
	v_cvt_pk_bf16_f32 v177, v116, v117
	global_store_dwordx4 v[148:149], v[174:177], off sc1
	v_cvt_pk_bf16_f32 v178, v94, v95
	v_cvt_pk_bf16_f32 v179, v96, v97
	v_cvt_pk_bf16_f32 v180, v90, v91
	v_cvt_pk_bf16_f32 v181, v92, v93
	global_store_dwordx4 v[148:149], v[178:181], off offset:256 sc1
	v_mov_b32_e32 v150, 0x28000
	v_mov_b32_e32 v151, 0
	v_lshl_add_u64 v[150:151], v[218:219], 0, v[150:151]
	v_cvt_pk_bf16_f32 v182, v62, v63
	v_cvt_pk_bf16_f32 v183, v64, v65
	v_cvt_pk_bf16_f32 v184, v58, v59
	v_cvt_pk_bf16_f32 v185, v60, v61
	global_store_dwordx4 v[150:151], v[182:185], off sc1
	v_cvt_pk_bf16_f32 v186, v46, v47
	v_cvt_pk_bf16_f32 v187, v48, v49
	v_cvt_pk_bf16_f32 v188, v42, v43
	v_cvt_pk_bf16_f32 v189, v44, v45
	global_store_dwordx4 v[150:151], v[186:189], off offset:256 sc1
	v_mov_b32_e32 v152, 0x30000
	v_mov_b32_e32 v153, 0
	v_lshl_add_u64 v[152:153], v[218:219], 0, v[152:153]
	v_cvt_pk_bf16_f32 v190, v54, v55
	v_cvt_pk_bf16_f32 v191, v56, v57
	v_cvt_pk_bf16_f32 v192, v50, v51
	v_cvt_pk_bf16_f32 v193, v52, v53
	global_store_dwordx4 v[152:153], v[190:193], off sc1
	v_cvt_pk_bf16_f32 v194, v30, v31
	v_cvt_pk_bf16_f32 v195, v32, v33
	v_cvt_pk_bf16_f32 v196, v26, v27
	v_cvt_pk_bf16_f32 v197, v28, v29
	global_store_dwordx4 v[152:153], v[194:197], off offset:256 sc1
	s_cmp_eq_u32 s12, 0
	s_cbranch_scc1 .Lp3_epi_done
	v_mov_b32_e32 v154, 0x10000
	v_mov_b32_e32 v155, 0
	v_lshl_add_u64 v[154:155], v[218:219], 0, v[154:155]
	v_cvt_pk_bf16_f32 v198, v102, v103
	v_cvt_pk_bf16_f32 v199, v104, v105
	v_cvt_pk_bf16_f32 v200, v98, v99
	v_cvt_pk_bf16_f32 v201, v100, v101
	global_store_dwordx4 v[154:155], v[198:201], off sc1
	v_cvt_pk_bf16_f32 v202, v78, v79
	v_cvt_pk_bf16_f32 v203, v80, v81
	v_cvt_pk_bf16_f32 v204, v74, v75
	v_cvt_pk_bf16_f32 v205, v76, v77
	global_store_dwordx4 v[154:155], v[202:205], off offset:256 sc1
	v_mov_b32_e32 v156, 0x38000
	v_mov_b32_e32 v157, 0
	v_lshl_add_u64 v[156:157], v[218:219], 0, v[156:157]
	v_cvt_pk_bf16_f32 v206, v38, v39
	v_cvt_pk_bf16_f32 v207, v40, v41
	v_cvt_pk_bf16_f32 v208, v34, v35
	v_cvt_pk_bf16_f32 v209, v36, v37
	global_store_dwordx4 v[156:157], v[206:209], off sc1
	v_cvt_pk_bf16_f32 v210, v14, v15
	v_cvt_pk_bf16_f32 v211, v16, v17
	v_cvt_pk_bf16_f32 v212, v10, v11
	v_cvt_pk_bf16_f32 v213, v12, v13
	global_store_dwordx4 v[156:157], v[210:213], off offset:256 sc1

.LBB0_837:
	s_mul_i32 s98, s24, 0xa0
	v_lshl_or_b32 v216, s73, 8, v143
	v_add_u32_e32 v214, s98, v1
	v_ashrrev_i32_e32 v217, 31, v216
	v_ashrrev_i32_e32 v215, 31, v214
	v_lshlrev_b64 v[216:217], 1, v[216:217]
	v_lshlrev_b64 v[218:219], 11, v[214:215]
	v_lshl_add_u64 v[218:219], s[42:43], 0, v[218:219]
	v_lshl_add_u64 v[218:219], v[218:219], 0, v[216:217]
	v_cvt_pk_bf16_f32 v166, v126, v127
	v_cvt_pk_bf16_f32 v167, v128, v129
	v_cvt_pk_bf16_f32 v168, v122, v123
	v_cvt_pk_bf16_f32 v169, v124, v125
	global_store_dwordx4 v[218:219], v[166:169], off sc1
	v_cvt_pk_bf16_f32 v170, v110, v111
	v_cvt_pk_bf16_f32 v171, v112, v113
	v_cvt_pk_bf16_f32 v172, v106, v107
	v_cvt_pk_bf16_f32 v173, v108, v109
	global_store_dwordx4 v[218:219], v[170:173], off offset:256 sc1
	v_mov_b32_e32 v148, 0x8000
	v_mov_b32_e32 v149, 0
	v_lshl_add_u64 v[148:149], v[218:219], 0, v[148:149]
	v_cvt_pk_bf16_f32 v174, v118, v119
	v_cvt_pk_bf16_f32 v175, v120, v121
	v_cvt_pk_bf16_f32 v176, v114, v115
	v_cvt_pk_bf16_f32 v177, v116, v117
	global_store_dwordx4 v[148:149], v[174:177], off sc1
	v_cvt_pk_bf16_f32 v178, v94, v95
	v_cvt_pk_bf16_f32 v179, v96, v97
	v_cvt_pk_bf16_f32 v180, v90, v91
	v_cvt_pk_bf16_f32 v181, v92, v93
	global_store_dwordx4 v[148:149], v[178:181], off offset:256 sc1
	v_mov_b32_e32 v150, 0x28000
	v_mov_b32_e32 v151, 0
	v_lshl_add_u64 v[150:151], v[218:219], 0, v[150:151]
	v_cvt_pk_bf16_f32 v182, v62, v63
	v_cvt_pk_bf16_f32 v183, v64, v65
	v_cvt_pk_bf16_f32 v184, v58, v59
	v_cvt_pk_bf16_f32 v185, v60, v61
	global_store_dwordx4 v[150:151], v[182:185], off sc1
	v_cvt_pk_bf16_f32 v186, v46, v47
	v_cvt_pk_bf16_f32 v187, v48, v49
	v_cvt_pk_bf16_f32 v188, v42, v43
	v_cvt_pk_bf16_f32 v189, v44, v45
	global_store_dwordx4 v[150:151], v[186:189], off offset:256 sc1
	v_mov_b32_e32 v152, 0x30000
	v_mov_b32_e32 v153, 0
	v_lshl_add_u64 v[152:153], v[218:219], 0, v[152:153]
	v_cvt_pk_bf16_f32 v190, v54, v55
	v_cvt_pk_bf16_f32 v191, v56, v57
	v_cvt_pk_bf16_f32 v192, v50, v51
	v_cvt_pk_bf16_f32 v193, v52, v53
	global_store_dwordx4 v[152:153], v[190:193], off sc1
	v_cvt_pk_bf16_f32 v194, v30, v31
	v_cvt_pk_bf16_f32 v195, v32, v33
	v_cvt_pk_bf16_f32 v196, v26, v27
	v_cvt_pk_bf16_f32 v197, v28, v29
	global_store_dwordx4 v[152:153], v[194:197], off offset:256 sc1
	s_cmp_eq_u32 s12, 0
	s_cbranch_scc1 .Lp7_epi_done
	v_mov_b32_e32 v154, 0x10000
	v_mov_b32_e32 v155, 0
	v_lshl_add_u64 v[154:155], v[218:219], 0, v[154:155]
	v_cvt_pk_bf16_f32 v198, v102, v103
	v_cvt_pk_bf16_f32 v199, v104, v105
	v_cvt_pk_bf16_f32 v200, v98, v99
	v_cvt_pk_bf16_f32 v201, v100, v101
	global_store_dwordx4 v[154:155], v[198:201], off sc1
	v_cvt_pk_bf16_f32 v202, v78, v79
	v_cvt_pk_bf16_f32 v203, v80, v81
	v_cvt_pk_bf16_f32 v204, v74, v75
	v_cvt_pk_bf16_f32 v205, v76, v77
	global_store_dwordx4 v[154:155], v[202:205], off offset:256 sc1
	v_mov_b32_e32 v156, 0x38000
	v_mov_b32_e32 v157, 0
	v_lshl_add_u64 v[156:157], v[218:219], 0, v[156:157]
	v_cvt_pk_bf16_f32 v206, v38, v39
	v_cvt_pk_bf16_f32 v207, v40, v41
	v_cvt_pk_bf16_f32 v208, v34, v35
	v_cvt_pk_bf16_f32 v209, v36, v37
	global_store_dwordx4 v[156:157], v[206:209], off sc1
	v_cvt_pk_bf16_f32 v210, v14, v15
	v_cvt_pk_bf16_f32 v211, v16, v17
	v_cvt_pk_bf16_f32 v212, v10, v11
	v_cvt_pk_bf16_f32 v213, v12, v13
	global_store_dwordx4 v[156:157], v[210:213], off offset:256 sc1

.LBB0_980:
	v_mul_f32_e32 v149, 0xbfb8aa3b, v126
	v_exp_f32_e32 v150, v149
	v_mul_f32_e32 v149, 0xbfb8aa3b, v127
	v_pk_mul_f32 v[122:123], v[126:127], v[122:123]
	v_mul_f32_e32 v126, 0xbfb8aa3b, v128
	v_mul_f32_e32 v127, 0xbfb8aa3b, v129
	v_exp_f32_e32 v126, v126
	v_exp_f32_e32 v127, v127
	v_pk_mul_f32 v[124:125], v[128:129], v[124:125]
	v_mul_f32_e32 v129, 0xbfb8aa3b, v119
	v_add_f32_e32 v126, 1.0, v126
	v_add_f32_e32 v127, 1.0, v127
	v_rcp_f32_e32 v126, v126
	v_rcp_f32_e32 v127, v127
	v_pk_mul_f32 v[114:115], v[118:119], v[114:115]
	v_pk_mul_f32 v[106:107], v[110:111], v[106:107]
	v_pk_mul_f32 v[108:109], v[112:113], v[108:109]
	v_pk_mul_f32 v[124:125], v[126:127], v[124:125]
	v_pk_mul_f32 v[100:101], v[104:105], v[100:101]
	v_cvt_pk_bf16_f32 v119, v124, v125
	v_mul_f32_e32 v124, 0xbfb8aa3b, v110
	v_mul_f32_e32 v125, 0xbfb8aa3b, v111
	v_mul_f32_e32 v110, 0xbfb8aa3b, v112
	v_mul_f32_e32 v111, 0xbfb8aa3b, v113
	v_exp_f32_e32 v110, v110
	v_exp_f32_e32 v111, v111
	v_mul_f32_e32 v112, 0xbfb8aa3b, v102
	v_mul_f32_e32 v113, 0xbfb8aa3b, v103
	v_add_f32_e32 v110, 1.0, v110
	v_add_f32_e32 v111, 1.0, v111
	v_rcp_f32_e32 v110, v110
	v_rcp_f32_e32 v111, v111
	v_exp_f32_e32 v112, v112
	v_exp_f32_e32 v113, v113
	v_pk_mul_f32 v[90:91], v[94:95], v[90:91]
	v_pk_mul_f32 v[108:109], v[110:111], v[108:109]
	v_add_f32_e32 v110, 1.0, v112
	v_add_f32_e32 v111, 1.0, v113
	v_mul_f32_e32 v112, 0xbfb8aa3b, v104
	v_mul_f32_e32 v113, 0xbfb8aa3b, v105
	v_exp_f32_e32 v112, v112
	v_exp_f32_e32 v113, v113
	v_mul_f32_e32 v128, 0xbfb8aa3b, v118
	v_pk_mul_f32 v[92:93], v[96:97], v[92:93]
	v_add_f32_e32 v112, 1.0, v112
	v_add_f32_e32 v113, 1.0, v113
	v_rcp_f32_e32 v112, v112
	v_rcp_f32_e32 v113, v113
	v_exp_f32_e32 v128, v128
	v_exp_f32_e32 v129, v129
	v_exp_f32_e32 v151, v149
	v_pk_mul_f32 v[104:105], v[112:113], v[100:101]
	v_add_f32_e32 v126, 1.0, v128
	v_cvt_pk_bf16_f32 v101, v104, v105
	v_mul_f32_e32 v104, 0xbfb8aa3b, v94
	v_mul_f32_e32 v105, 0xbfb8aa3b, v95
	v_mul_f32_e32 v94, 0xbfb8aa3b, v96
	v_mul_f32_e32 v95, 0xbfb8aa3b, v97
	v_exp_f32_e32 v94, v94
	v_exp_f32_e32 v95, v95
	v_mul_f32_e32 v96, 0xbfb8aa3b, v86
	v_mul_f32_e32 v97, 0xbfb8aa3b, v87
	v_add_f32_e32 v94, 1.0, v94
	v_add_f32_e32 v95, 1.0, v95
	v_rcp_f32_e32 v94, v94
	v_rcp_f32_e32 v95, v95
	v_exp_f32_e32 v96, v96
	v_exp_f32_e32 v97, v97
	v_add_f32_e32 v127, 1.0, v129
	v_mul_f32_e32 v128, 0xbfb8aa3b, v120
	v_mul_f32_e32 v129, 0xbfb8aa3b, v121
	v_pk_mul_f32 v[92:93], v[94:95], v[92:93]
	v_add_f32_e32 v94, 1.0, v96
	v_add_f32_e32 v95, 1.0, v97
	v_mul_f32_e32 v96, 0xbfb8aa3b, v88
	v_mul_f32_e32 v97, 0xbfb8aa3b, v89
	v_exp_f32_e32 v128, v128
	v_exp_f32_e32 v129, v129
	v_exp_f32_e32 v96, v96
	v_exp_f32_e32 v97, v97
	v_add_f32_e32 v150, 1.0, v150
	v_add_f32_e32 v151, 1.0, v151
	v_rcp_f32_e32 v126, v126
	v_rcp_f32_e32 v127, v127
	v_add_f32_e32 v128, 1.0, v128
	v_add_f32_e32 v129, 1.0, v129
	v_add_f32_e32 v96, 1.0, v96
	v_add_f32_e32 v97, 1.0, v97
	v_rcp_f32_e32 v150, v150
	v_rcp_f32_e32 v151, v151
	v_rcp_f32_e32 v128, v128
	v_rcp_f32_e32 v129, v129
	v_rcp_f32_e32 v96, v96
	v_rcp_f32_e32 v97, v97
	v_lshl_or_b32 v148, s59, 7, v143
	v_pk_mul_f32 v[116:117], v[120:121], v[116:117]
	v_pk_mul_f32 v[114:115], v[126:127], v[114:115]
	v_exp_f32_e32 v124, v124
	v_exp_f32_e32 v125, v125
	v_pk_mul_f32 v[84:85], v[88:89], v[84:85]
	v_lshl_add_u32 v147, s22, 8, v1
	v_ashrrev_i32_e32 v149, 31, v148
	v_pk_mul_f32 v[122:123], v[150:151], v[122:123]
	v_pk_mul_f32 v[116:117], v[128:129], v[116:117]
	v_cvt_pk_bf16_f32 v120, v114, v115
	v_mov_b64_e32 v[114:115], s[40:41]
	v_pk_mul_f32 v[88:89], v[96:97], v[84:85]
	v_cvt_pk_bf16_f32 v118, v122, v123
	v_cvt_pk_bf16_f32 v121, v116, v117
	v_mad_i64_i32 v[122:123], s[24:25], v147, s58, v[114:115]
	v_lshlrev_b64 v[116:117], 1, v[148:149]
	v_cvt_pk_bf16_f32 v85, v88, v89
	v_mul_f32_e32 v88, 0xbfb8aa3b, v78
	v_mul_f32_e32 v89, 0xbfb8aa3b, v79
	v_pk_mul_f32 v[74:75], v[78:79], v[74:75]
	v_mul_f32_e32 v78, 0xbfb8aa3b, v80
	v_mul_f32_e32 v79, 0xbfb8aa3b, v81
	v_lshl_add_u64 v[122:123], v[122:123], 0, v[116:117]
	v_rcp_f32_e32 v110, v110
	v_rcp_f32_e32 v111, v111
	v_exp_f32_e32 v78, v78
	v_exp_f32_e32 v79, v79
	global_store_dwordx4 v[122:123], v[118:121], off sc1
	v_pk_mul_f32 v[98:99], v[102:103], v[98:99]
	v_exp_f32_e32 v104, v104
	v_add_f32_e32 v118, 1.0, v124
	v_add_f32_e32 v119, 1.0, v125
	v_rcp_f32_e32 v118, v118
	v_rcp_f32_e32 v119, v119
	v_pk_mul_f32 v[102:103], v[110:111], v[98:99]
	v_exp_f32_e32 v105, v105
	v_pk_mul_f32 v[76:77], v[80:81], v[76:77]
	v_add_f32_e32 v78, 1.0, v78
	v_add_f32_e32 v79, 1.0, v79
	v_mul_f32_e32 v80, 0xbfb8aa3b, v70
	v_mul_f32_e32 v81, 0xbfb8aa3b, v71
	v_cvt_pk_bf16_f32 v100, v102, v103
	v_or_b32_e32 v102, 16, v147
	v_rcp_f32_e32 v78, v78
	v_rcp_f32_e32 v79, v79
	v_exp_f32_e32 v80, v80
	v_exp_f32_e32 v81, v81
	v_pk_mul_f32 v[106:107], v[118:119], v[106:107]
	v_mad_i64_i32 v[102:103], s[24:25], v102, s58, v[114:115]
	v_cvt_pk_bf16_f32 v98, v106, v107
	v_cvt_pk_bf16_f32 v99, v108, v109
	v_lshl_add_u64 v[102:103], v[102:103], 0, v[116:117]
	v_rcp_f32_e32 v94, v94
	v_rcp_f32_e32 v95, v95
	global_store_dwordx4 v[102:103], v[98:101], off sc1
	v_pk_mul_f32 v[76:77], v[78:79], v[76:77]
	v_add_f32_e32 v78, 1.0, v80
	v_add_f32_e32 v98, 1.0, v104
	v_add_f32_e32 v99, 1.0, v105
	v_rcp_f32_e32 v98, v98
	v_rcp_f32_e32 v99, v99
	v_add_f32_e32 v79, 1.0, v81
	v_mul_f32_e32 v80, 0xbfb8aa3b, v72
	v_mul_f32_e32 v81, 0xbfb8aa3b, v73
	v_pk_mul_f32 v[82:83], v[86:87], v[82:83]
	v_exp_f32_e32 v80, v80
	v_exp_f32_e32 v81, v81
	v_pk_mul_f32 v[86:87], v[94:95], v[82:83]
	v_exp_f32_e32 v88, v88
	v_exp_f32_e32 v89, v89
	v_cvt_pk_bf16_f32 v84, v86, v87
	v_or_b32_e32 v86, 32, v147
	v_pk_mul_f32 v[90:91], v[98:99], v[90:91]
	v_mad_i64_i32 v[86:87], s[24:25], v86, s58, v[114:115]
	v_cvt_pk_bf16_f32 v82, v90, v91
	v_cvt_pk_bf16_f32 v83, v92, v93
	v_lshl_add_u64 v[86:87], v[86:87], 0, v[116:117]
	v_rcp_f32_e32 v78, v78
	v_rcp_f32_e32 v79, v79
	v_add_f32_e32 v80, 1.0, v80
	v_add_f32_e32 v81, 1.0, v81
	global_store_dwordx4 v[86:87], v[82:85], off sc1
	v_rcp_f32_e32 v80, v80
	v_rcp_f32_e32 v81, v81
	v_add_f32_e32 v82, 1.0, v88
	v_add_f32_e32 v83, 1.0, v89
	v_rcp_f32_e32 v82, v82
	v_rcp_f32_e32 v83, v83
	v_pk_mul_f32 v[66:67], v[70:71], v[66:67]
	v_pk_mul_f32 v[68:69], v[72:73], v[68:69]
	v_pk_mul_f32 v[70:71], v[78:79], v[66:67]
	v_pk_mul_f32 v[72:73], v[80:81], v[68:69]
	v_cvt_pk_bf16_f32 v68, v70, v71
	v_or_b32_e32 v70, 48, v147
	v_pk_mul_f32 v[74:75], v[82:83], v[74:75]
	v_mad_i64_i32 v[70:71], s[24:25], v70, s58, v[114:115]
	v_cvt_pk_bf16_f32 v66, v74, v75
	v_cvt_pk_bf16_f32 v67, v76, v77
	v_cvt_pk_bf16_f32 v69, v72, v73
	v_lshl_add_u64 v[70:71], v[70:71], 0, v[116:117]
	global_store_dwordx4 v[70:71], v[66:69], off sc1
	v_pk_mul_f32 v[58:59], v[62:63], v[58:59]
	v_pk_mul_f32 v[60:61], v[64:65], v[60:61]
	v_mul_f32_e32 v66, 0xbfb8aa3b, v62
	v_mul_f32_e32 v67, 0xbfb8aa3b, v63
	v_mul_f32_e32 v62, 0xbfb8aa3b, v64
	v_mul_f32_e32 v63, 0xbfb8aa3b, v65
	v_exp_f32_e32 v62, v62
	v_exp_f32_e32 v63, v63
	v_mul_f32_e32 v64, 0xbfb8aa3b, v54
	v_mul_f32_e32 v65, 0xbfb8aa3b, v55
	v_add_f32_e32 v62, 1.0, v62
	v_add_f32_e32 v63, 1.0, v63
	v_rcp_f32_e32 v62, v62
	v_rcp_f32_e32 v63, v63
	v_exp_f32_e32 v64, v64
	v_exp_f32_e32 v65, v65
	v_pk_mul_f32 v[52:53], v[56:57], v[52:53]
	v_pk_mul_f32 v[60:61], v[62:63], v[60:61]
	v_add_f32_e32 v62, 1.0, v64
	v_add_f32_e32 v63, 1.0, v65
	v_mul_f32_e32 v64, 0xbfb8aa3b, v56
	v_mul_f32_e32 v65, 0xbfb8aa3b, v57
	v_exp_f32_e32 v64, v64
	v_exp_f32_e32 v65, v65
	v_pk_mul_f32 v[42:43], v[46:47], v[42:43]
	v_pk_mul_f32 v[44:45], v[48:49], v[44:45]
	v_add_f32_e32 v64, 1.0, v64
	v_add_f32_e32 v65, 1.0, v65
	v_rcp_f32_e32 v64, v64
	v_rcp_f32_e32 v65, v65
	v_pk_mul_f32 v[36:37], v[40:41], v[36:37]
	v_pk_mul_f32 v[26:27], v[30:31], v[26:27]
	v_pk_mul_f32 v[28:29], v[32:33], v[28:29]
	v_pk_mul_f32 v[56:57], v[64:65], v[52:53]
	v_exp_f32_e32 v66, v66
	v_cvt_pk_bf16_f32 v53, v56, v57
	v_mul_f32_e32 v56, 0xbfb8aa3b, v46
	v_mul_f32_e32 v57, 0xbfb8aa3b, v47
	v_mul_f32_e32 v46, 0xbfb8aa3b, v48
	v_mul_f32_e32 v47, 0xbfb8aa3b, v49
	v_exp_f32_e32 v46, v46
	v_exp_f32_e32 v47, v47
	v_mul_f32_e32 v48, 0xbfb8aa3b, v38
	v_mul_f32_e32 v49, 0xbfb8aa3b, v39
	v_add_f32_e32 v46, 1.0, v46
	v_add_f32_e32 v47, 1.0, v47
	v_rcp_f32_e32 v46, v46
	v_rcp_f32_e32 v47, v47
	v_exp_f32_e32 v48, v48
	v_exp_f32_e32 v49, v49
	v_exp_f32_e32 v67, v67
	v_pk_mul_f32 v[44:45], v[46:47], v[44:45]
	v_add_f32_e32 v46, 1.0, v48
	v_add_f32_e32 v47, 1.0, v49
	v_mul_f32_e32 v48, 0xbfb8aa3b, v40
	v_mul_f32_e32 v49, 0xbfb8aa3b, v41
	v_exp_f32_e32 v48, v48
	v_exp_f32_e32 v49, v49
	v_add_f32_e32 v66, 1.0, v66
	v_add_f32_e32 v67, 1.0, v67
	v_add_f32_e32 v48, 1.0, v48
	v_add_f32_e32 v49, 1.0, v49
	v_rcp_f32_e32 v48, v48
	v_rcp_f32_e32 v49, v49
	v_rcp_f32_e32 v62, v62
	v_rcp_f32_e32 v63, v63
	v_rcp_f32_e32 v66, v66
	v_pk_mul_f32 v[40:41], v[48:49], v[36:37]
	v_rcp_f32_e32 v67, v67
	v_cvt_pk_bf16_f32 v37, v40, v41
	v_mul_f32_e32 v40, 0xbfb8aa3b, v30
	v_mul_f32_e32 v41, 0xbfb8aa3b, v31
	v_mul_f32_e32 v30, 0xbfb8aa3b, v32
	v_mul_f32_e32 v31, 0xbfb8aa3b, v33
	v_exp_f32_e32 v30, v30
	v_exp_f32_e32 v31, v31
	v_mul_f32_e32 v32, 0xbfb8aa3b, v22
	v_mul_f32_e32 v33, 0xbfb8aa3b, v23
	v_add_f32_e32 v30, 1.0, v30
	v_add_f32_e32 v31, 1.0, v31
	v_rcp_f32_e32 v30, v30
	v_rcp_f32_e32 v31, v31
	v_exp_f32_e32 v32, v32
	v_exp_f32_e32 v33, v33
	v_pk_mul_f32 v[50:51], v[54:55], v[50:51]
	v_pk_mul_f32 v[28:29], v[30:31], v[28:29]
	v_add_f32_e32 v30, 1.0, v32
	v_add_f32_e32 v31, 1.0, v33
	v_mul_f32_e32 v32, 0xbfb8aa3b, v24
	v_mul_f32_e32 v33, 0xbfb8aa3b, v25
	v_exp_f32_e32 v32, v32
	v_exp_f32_e32 v33, v33
	v_exp_f32_e32 v56, v56
	v_exp_f32_e32 v57, v57
	v_add_f32_e32 v32, 1.0, v32
	v_add_f32_e32 v33, 1.0, v33
	v_rcp_f32_e32 v32, v32
	v_rcp_f32_e32 v33, v33
	v_pk_mul_f32 v[20:21], v[24:25], v[20:21]
	v_add_u32_e32 v68, 0x80, v147
	v_pk_mul_f32 v[54:55], v[62:63], v[50:51]
	v_pk_mul_f32 v[24:25], v[32:33], v[20:21]
	v_pk_mul_f32 v[58:59], v[66:67], v[58:59]
	v_cvt_pk_bf16_f32 v52, v54, v55
	v_mad_i64_i32 v[54:55], s[24:25], v68, s58, v[114:115]
	v_cvt_pk_bf16_f32 v21, v24, v25
	v_mul_f32_e32 v24, 0xbfb8aa3b, v14
	v_mul_f32_e32 v25, 0xbfb8aa3b, v15
	v_pk_mul_f32 v[10:11], v[14:15], v[10:11]
	v_mul_f32_e32 v14, 0xbfb8aa3b, v16
	v_mul_f32_e32 v15, 0xbfb8aa3b, v17
	v_cvt_pk_bf16_f32 v50, v58, v59
	v_cvt_pk_bf16_f32 v51, v60, v61
	v_lshl_add_u64 v[54:55], v[54:55], 0, v[116:117]
	v_rcp_f32_e32 v46, v46
	v_rcp_f32_e32 v47, v47
	v_exp_f32_e32 v14, v14
	v_exp_f32_e32 v15, v15
	global_store_dwordx4 v[54:55], v[50:53], off sc1
	v_pk_mul_f32 v[34:35], v[38:39], v[34:35]
	v_exp_f32_e32 v40, v40
	v_add_f32_e32 v50, 1.0, v56
	v_add_f32_e32 v51, 1.0, v57
	v_rcp_f32_e32 v50, v50
	v_rcp_f32_e32 v51, v51
	v_pk_mul_f32 v[38:39], v[46:47], v[34:35]
	v_exp_f32_e32 v41, v41
	v_pk_mul_f32 v[12:13], v[16:17], v[12:13]
	v_add_f32_e32 v14, 1.0, v14
	v_add_f32_e32 v15, 1.0, v15
	v_mul_f32_e32 v16, 0xbfb8aa3b, v6
	v_mul_f32_e32 v17, 0xbfb8aa3b, v7
	v_cvt_pk_bf16_f32 v36, v38, v39
	v_add_u32_e32 v38, 0x90, v147
	v_rcp_f32_e32 v14, v14
	v_rcp_f32_e32 v15, v15
	v_exp_f32_e32 v16, v16
	v_exp_f32_e32 v17, v17
	v_pk_mul_f32 v[42:43], v[50:51], v[42:43]
	v_mad_i64_i32 v[38:39], s[24:25], v38, s58, v[114:115]
	v_cvt_pk_bf16_f32 v34, v42, v43
	v_cvt_pk_bf16_f32 v35, v44, v45
	v_lshl_add_u64 v[38:39], v[38:39], 0, v[116:117]
	v_rcp_f32_e32 v30, v30
	v_rcp_f32_e32 v31, v31
	global_store_dwordx4 v[38:39], v[34:37], off sc1
	v_pk_mul_f32 v[12:13], v[14:15], v[12:13]
	v_add_f32_e32 v14, 1.0, v16
	v_add_f32_e32 v34, 1.0, v40
	v_add_f32_e32 v35, 1.0, v41
	v_rcp_f32_e32 v34, v34
	v_rcp_f32_e32 v35, v35
	v_add_f32_e32 v15, 1.0, v17
	v_mul_f32_e32 v16, 0xbfb8aa3b, v8
	v_mul_f32_e32 v17, 0xbfb8aa3b, v9
	v_pk_mul_f32 v[18:19], v[22:23], v[18:19]
	v_exp_f32_e32 v16, v16
	v_exp_f32_e32 v17, v17
	v_pk_mul_f32 v[22:23], v[30:31], v[18:19]
	v_exp_f32_e32 v24, v24
	v_exp_f32_e32 v25, v25
	v_cvt_pk_bf16_f32 v20, v22, v23
	v_add_u32_e32 v22, 0xa0, v147
	v_pk_mul_f32 v[26:27], v[34:35], v[26:27]
	v_mad_i64_i32 v[22:23], s[24:25], v22, s58, v[114:115]
	v_cvt_pk_bf16_f32 v18, v26, v27
	v_cvt_pk_bf16_f32 v19, v28, v29
	v_lshl_add_u64 v[22:23], v[22:23], 0, v[116:117]
	v_rcp_f32_e32 v14, v14
	v_rcp_f32_e32 v15, v15
	v_add_f32_e32 v16, 1.0, v16
	v_add_f32_e32 v17, 1.0, v17
	global_store_dwordx4 v[22:23], v[18:21], off sc1
	v_rcp_f32_e32 v16, v16
	v_rcp_f32_e32 v17, v17
	v_add_f32_e32 v18, 1.0, v24
	v_add_f32_e32 v19, 1.0, v25
	v_rcp_f32_e32 v18, v18
	v_rcp_f32_e32 v19, v19
	v_pk_mul_f32 v[2:3], v[6:7], v[2:3]
	v_pk_mul_f32 v[4:5], v[8:9], v[4:5]
	v_pk_mul_f32 v[6:7], v[14:15], v[2:3]
	v_pk_mul_f32 v[8:9], v[16:17], v[4:5]
	v_cvt_pk_bf16_f32 v4, v6, v7
	v_add_u32_e32 v6, 0xb0, v147
	v_pk_mul_f32 v[10:11], v[18:19], v[10:11]
	v_mad_i64_i32 v[6:7], s[24:25], v6, s58, v[114:115]
	v_cvt_pk_bf16_f32 v2, v10, v11
	v_cvt_pk_bf16_f32 v3, v12, v13
	v_cvt_pk_bf16_f32 v5, v8, v9
	v_lshl_add_u64 v[6:7], v[6:7], 0, v[116:117]
	s_andn2_b64 vcc, exec, s[0:1]
	s_mov_b64 s[0:1], -1
	global_store_dwordx4 v[6:7], v[2:5], off sc1
	s_cbranch_vccnz .LBB0_973
	s_andn2_b64 vcc, exec, s[6:7]
	s_cbranch_vccnz .LBB0_972
	s_barrier
	s_branch .LBB0_972

.LBB0_1061:
	s_mul_i32 s98, s66, 0xa0
	v_lshl_or_b32 v216, s67, 8, v142
	v_add_u32_e32 v214, s98, v140
	v_ashrrev_i32_e32 v217, 31, v216
	v_ashrrev_i32_e32 v215, 31, v214
	v_lshlrev_b64 v[216:217], 1, v[216:217]
	v_lshlrev_b64 v[218:219], 11, v[214:215]
	v_lshl_add_u64 v[218:219], s[42:43], 0, v[218:219]
	v_lshl_add_u64 v[218:219], v[218:219], 0, v[216:217]
	v_cvt_pk_bf16_f32 v166, v124, v125
	v_cvt_pk_bf16_f32 v167, v126, v127
	v_cvt_pk_bf16_f32 v168, v120, v121
	v_cvt_pk_bf16_f32 v169, v122, v123
	global_store_dwordx4 v[218:219], v[166:169], off sc1
	v_cvt_pk_bf16_f32 v170, v108, v109
	v_cvt_pk_bf16_f32 v171, v110, v111
	v_cvt_pk_bf16_f32 v172, v104, v105
	v_cvt_pk_bf16_f32 v173, v106, v107
	global_store_dwordx4 v[218:219], v[170:173], off offset:256 sc1
	v_mov_b32_e32 v148, 0x8000
	v_mov_b32_e32 v149, 0
	v_lshl_add_u64 v[148:149], v[218:219], 0, v[148:149]
	v_cvt_pk_bf16_f32 v174, v116, v117
	v_cvt_pk_bf16_f32 v175, v118, v119
	v_cvt_pk_bf16_f32 v176, v112, v113
	v_cvt_pk_bf16_f32 v177, v114, v115
	global_store_dwordx4 v[148:149], v[174:177], off sc1
	v_cvt_pk_bf16_f32 v178, v92, v93
	v_cvt_pk_bf16_f32 v179, v94, v95
	v_cvt_pk_bf16_f32 v180, v88, v89
	v_cvt_pk_bf16_f32 v181, v90, v91
	global_store_dwordx4 v[148:149], v[178:181], off offset:256 sc1
	v_mov_b32_e32 v150, 0x28000
	v_mov_b32_e32 v151, 0
	v_lshl_add_u64 v[150:151], v[218:219], 0, v[150:151]
	v_cvt_pk_bf16_f32 v182, v60, v61
	v_cvt_pk_bf16_f32 v183, v62, v63
	v_cvt_pk_bf16_f32 v184, v56, v57
	v_cvt_pk_bf16_f32 v185, v58, v59
	global_store_dwordx4 v[150:151], v[182:185], off sc1
	v_cvt_pk_bf16_f32 v186, v44, v45
	v_cvt_pk_bf16_f32 v187, v46, v47
	v_cvt_pk_bf16_f32 v188, v40, v41
	v_cvt_pk_bf16_f32 v189, v42, v43
	global_store_dwordx4 v[150:151], v[186:189], off offset:256 sc1
	v_mov_b32_e32 v152, 0x30000
	v_mov_b32_e32 v153, 0
	v_lshl_add_u64 v[152:153], v[218:219], 0, v[152:153]
	v_cvt_pk_bf16_f32 v190, v52, v53
	v_cvt_pk_bf16_f32 v191, v54, v55
	v_cvt_pk_bf16_f32 v192, v48, v49
	v_cvt_pk_bf16_f32 v193, v50, v51
	global_store_dwordx4 v[152:153], v[190:193], off sc1
	v_cvt_pk_bf16_f32 v194, v28, v29
	v_cvt_pk_bf16_f32 v195, v30, v31
	v_cvt_pk_bf16_f32 v196, v24, v25
	v_cvt_pk_bf16_f32 v197, v26, v27
	global_store_dwordx4 v[152:153], v[194:197], off offset:256 sc1
	s_cmp_eq_u32 s12, 0
	s_cbranch_scc1 .Lp10_epi_done
	v_mov_b32_e32 v154, 0x10000
	v_mov_b32_e32 v155, 0
	v_lshl_add_u64 v[154:155], v[218:219], 0, v[154:155]
	v_cvt_pk_bf16_f32 v198, v100, v101
	v_cvt_pk_bf16_f32 v199, v102, v103
	v_cvt_pk_bf16_f32 v200, v96, v97
	v_cvt_pk_bf16_f32 v201, v98, v99
	global_store_dwordx4 v[154:155], v[198:201], off sc1
	v_cvt_pk_bf16_f32 v202, v76, v77
	v_cvt_pk_bf16_f32 v203, v78, v79
	v_cvt_pk_bf16_f32 v204, v72, v73
	v_cvt_pk_bf16_f32 v205, v74, v75
	global_store_dwordx4 v[154:155], v[202:205], off offset:256 sc1
	v_mov_b32_e32 v156, 0x38000
	v_mov_b32_e32 v157, 0
	v_lshl_add_u64 v[156:157], v[218:219], 0, v[156:157]
	v_cvt_pk_bf16_f32 v206, v36, v37
	v_cvt_pk_bf16_f32 v207, v38, v39
	v_cvt_pk_bf16_f32 v208, v32, v33
	v_cvt_pk_bf16_f32 v209, v34, v35
	global_store_dwordx4 v[156:157], v[206:209], off sc1
	v_cvt_pk_bf16_f32 v210, v12, v13
	v_cvt_pk_bf16_f32 v211, v14, v15
	v_cvt_pk_bf16_f32 v212, v8, v9
	v_cvt_pk_bf16_f32 v213, v10, v11
	global_store_dwordx4 v[156:157], v[210:213], off offset:256 sc1
